# one static priority raise for waves 4-7 per GEMM phase (no per-segment toggling)
# baseline (speedup 1.0000x reference)
.LBB0_262:
	s_cmp_lt_i32 s48, 3
	s_cselect_b64 s[6:7], -1, 0
	s_add_u32 s58, s46, 0x8000000
	s_addc_u32 s59, s47, 0
	s_add_u32 s56, s46, 0x10000000
	s_addc_u32 s57, s47, 0
	s_and_b64 s[6:7], s[6:7], s[4:5]
	v_mov_b32_e32 v0, v190
	s_andn2_b64 vcc, exec, s[6:7]
	s_cbranch_vccnz .LBB0_309
	v_readlane_b32 s98, v247, 2
	s_cmp_lt_u32 s98, 4
	s_cbranch_scc1 .Lstatprio2
	s_setprio 1
.Lstatprio2:
	v_mov_b32_e32 v10, v190
	s_cmpk_gt_i32 s2, 0x47f
	v_readfirstlane_b32 s5, v10
	s_cbranch_scc1 .LBB0_285
	v_lshlrev_b32_e32 v0, 4, v10
	v_add_u32_e32 v1, 0x2000, v0
	v_ashrrev_i32_e32 v2, 31, v1
	v_lshrrev_b32_e32 v2, 22, v2
	v_add_u32_e32 v2, v1, v2
	v_ashrrev_i32_e32 v8, 10, v2
	v_mul_i32_i24_e32 v2, 0x400, v8
	v_sub_u32_e32 v1, v1, v2
	v_lshrrev_b32_e32 v2, 4, v1
	v_bitop3_b32 v1, v2, v1, 32 bitop3:0x6c
	v_ashrrev_i32_e32 v2, 31, v1
	v_lshrrev_b32_e32 v2, 26, v2
	v_add_u32_e32 v2, v1, v2
	v_lshlrev_b32_e32 v3, 3, v8
	v_ashrrev_i32_e32 v9, 6, v2
	v_and_b32_e32 v3, -16, v3
	v_add_u32_e32 v3, v9, v3
	v_and_b32_e32 v4, 3, v9
	s_mov_b32 s4, 0x1fffe0
	v_lshrrev_b32_e32 v5, 2, v3
	v_lshlrev_b32_e32 v6, 1, v3
	v_and_b32_e32 v2, 0xc0, v2
	v_and_or_b32 v4, v3, s4, v4
	v_and_b32_e32 v5, 4, v5
	v_and_b32_e32 v6, 24, v6
	v_sub_u32_e32 v1, v1, v2
	v_mov_b32_e32 v2, 1
	v_or3_b32 v4, v4, v5, v6
	v_lshlrev_b32_e32 v5, 5, v8
	v_ashrrev_i16_sdwa v1, v2, sext(v1) dst_sel:DWORD dst_unused:UNUSED_PAD src0_sel:DWORD src1_sel:BYTE_0
	v_and_b32_e32 v5, 32, v5
	v_bfe_i32 v11, v1, 0, 16
	v_add_lshl_u32 v1, v5, v11, 1
	v_lshl_add_u32 v128, v4, 11, v1
	v_lshl_add_u32 v130, v3, 11, v1
	v_bfe_i32 v1, v10, 27, 1
	v_lshrrev_b32_e32 v1, 22, v1
	v_add_u32_e32 v1, v0, v1
	v_and_b32_e32 v1, 0xfffffc00, v1
	v_sub_u32_e32 v0, v0, v1
	v_lshrrev_b32_e32 v1, 4, v0
	v_ashrrev_i32_e32 v3, 31, v10
	v_bitop3_b32 v0, v1, v0, 32 bitop3:0x6c
	v_lshrrev_b32_e32 v3, 26, v3
	v_ashrrev_i32_e32 v1, 31, v0
	v_add_u32_e32 v3, v10, v3
	v_lshrrev_b32_e32 v1, 26, v1
	v_ashrrev_i32_e32 v13, 6, v3
	v_add_u32_e32 v1, v0, v1
	v_lshlrev_b32_e32 v3, 3, v13
	s_add_u32 s66, s46, 0x1000000
	v_ashrrev_i32_e32 v12, 6, v1
	v_and_b32_e32 v3, -16, v3
	s_addc_u32 s67, s47, 0
	v_add_u32_e32 v3, v12, v3
	v_and_b32_e32 v4, 3, v12
	s_ashr_i32 s52, s2, 31
	v_and_or_b32 v4, v3, s4, v4
	s_lshr_b32 s4, s52, 29
	s_add_i32 s4, s2, s4
	s_ashr_i32 s10, s5, 6
	s_ashr_i32 s8, s4, 3
	s_and_b32 s4, s4, -8
	s_ashr_i32 s12, s5, 8
	s_lshl_b32 s68, s10, 10
	s_sub_i32 s4, s2, s4
	s_cmp_lt_i32 s4, 0
	s_movk_i32 s53, 0x91
	s_cselect_b32 s9, s53, 0x90
	s_mul_i32 s4, s9, s4
	s_add_i32 s4, s4, s8
	s_mul_hi_i32 s8, s4, 0x38e38e39
	s_lshr_b32 s9, s8, 31
	s_ashr_i32 s8, s8, 4
	s_add_i32 s8, s8, s9
	s_lshl_b32 s9, s8, 3
	s_mulk_i32 s8, 0x48
	s_sub_i32 s8, s4, s8
	s_bfe_i32 s4, s8, 0x80000
	s_bfe_u32 s4, s4, 0x3000c
	s_add_i32 s11, s8, s4
	s_bfe_i32 s4, s11, 0x80000
	s_and_b32 s11, s11, 0xf8
	s_sub_i32 s8, s8, s11
	s_sext_i32_i16 s4, s4
	s_sext_i32_i8 s8, s8
	v_lshrrev_b32_e32 v5, 2, v3
	v_lshlrev_b32_e32 v6, 1, v3
	v_and_b32_e32 v1, 0xc0, v1
	s_lshr_b32 s4, s4, 3
	s_add_i32 s42, s9, s8
	v_and_b32_e32 v5, 4, v5
	v_and_b32_e32 v6, 24, v6
	v_sub_u32_e32 v0, v0, v1
	s_ashr_i32 s43, s42, 31
	s_bfe_i64 s[14:15], s[4:5], 0x100000
	v_or3_b32 v4, v4, v5, v6
	v_lshlrev_b32_e32 v5, 5, v13
	v_ashrrev_i16_sdwa v0, v2, sext(v0) dst_sel:DWORD dst_unused:UNUSED_PAD src0_sel:DWORD src1_sel:BYTE_0
	s_lshl_b64 s[8:9], s[42:43], 19
	s_lshl_b64 s[14:15], s[14:15], 19
	v_and_b32_e32 v5, 32, v5
	v_bfe_i32 v14, v0, 0, 16
	s_add_u32 s62, s66, s14
	v_add_lshl_u32 v0, v5, v14, 1
	s_addc_u32 s63, s67, s15
	s_add_i32 s69, s68, 0
	v_lshl_add_u32 v132, v4, 11, v0
	s_add_i32 m0, s69, 0x10000
	v_lshl_add_u32 v134, v3, 11, v0
	global_load_lds_dwordx4 v132, s[62:63]
	s_add_i32 m0, s69, 0x12000
	s_add_u32 s14, s62, 0x40000
	global_load_lds_dwordx4 v128, s[62:63]
	s_addc_u32 s15, s63, 0
	s_add_i32 m0, s69, 0x14000
	v_mov_b32_e32 v133, 0
	global_load_lds_dwordx4 v132, s[14:15]
	s_add_i32 m0, s69, 0x16000
	s_add_u32 s60, s58, s8
	s_addc_u32 s61, s59, s9
	s_add_i32 s70, s69, 0x2000
	global_load_lds_dwordx4 v128, s[14:15]
	s_mov_b32 m0, s69
	s_add_u32 s8, s60, 0x40000
	global_load_lds_dwordx4 v134, s[60:61]
	s_mov_b32 m0, s70
	s_addc_u32 s9, s61, 0
	s_add_i32 s71, s69, 0x4000
	global_load_lds_dwordx4 v130, s[60:61]
	s_mov_b32 m0, s71
	s_add_i32 s72, s69, 0x6000
	global_load_lds_dwordx4 v134, s[8:9]
	s_mov_b32 m0, s72
	v_mov_b32_e32 v129, v133
	global_load_lds_dwordx4 v130, s[8:9]
	v_mov_b32_e32 v135, v133
	v_mov_b32_e32 v131, v133
	s_cmp_eq_u32 s12, 1
	s_mov_b32 s73, 0
	v_lshl_add_u64 v[6:7], s[62:63], 0, v[132:133]
	v_lshl_add_u64 v[4:5], s[62:63], 0, v[128:129]
	v_lshl_add_u64 v[0:1], s[60:61], 0, v[134:135]
	s_cselect_b64 s[8:9], -1, 0
	s_cmp_lg_u32 s12, 1
	v_lshl_add_u64 v[2:3], s[60:61], 0, v[130:131]
	s_cbranch_scc1 .LBB0_266
	s_barrier

.LBB0_309:
	s_setprio 0
	s_cmp_gt_i32 s49, 3
	s_cselect_b64 s[4:5], -1, 0
	s_and_b64 s[6:7], s[6:7], s[4:5]
	s_andn2_b64 vcc, exec, s[6:7]
	s_cbranch_vccnz .LBB0_363
	s_waitcnt vmcnt(0)
	s_waitcnt vmcnt(0)
	s_barrier
	s_and_saveexec_b64 s[6:7], s[44:45]
	s_cbranch_execz .LBB0_362
	s_add_i32 s8, 0, 0x21020
	v_mov_b32_e32 v0, s8
	s_waitcnt vmcnt(0) expcnt(0) lgkmcnt(0)
	ds_read_b32 v2, v0
	s_add_i32 s8, 0, 0x21024
	v_mov_b32_e32 v0, s8
	ds_read_b32 v0, v0
	s_waitcnt lgkmcnt(1)
	v_cmp_ne_u32_e32 vcc, 0, v2
	s_cbranch_vccnz .LBB0_326
	v_readlane_b32 s8, v247, 0
	v_readlane_b32 s9, v247, 1
	s_load_dwordx2 s[12:13], s[8:9], 0x4
	s_add_u32 s8, s46, 0x4200
	s_addc_u32 s9, s47, 0
	s_add_u32 s10, s46, 0x4400
	s_addc_u32 s11, s47, 0
	s_waitcnt lgkmcnt(0)
	s_mul_i32 s33, s12, s3
	s_add_u32 s12, s46, 0x4500
	s_mul_i32 s33, s33, s13
	s_addc_u32 s13, s47, 0
	s_add_u32 s14, s46, 0x4600
	s_addc_u32 s15, s47, 0
	s_add_u32 s16, s46, 0x4700
	s_addc_u32 s17, s47, 0
	s_add_u32 s18, s46, 0x4800
	s_addc_u32 s19, s47, 0
	s_add_u32 s20, s46, 0x4900
	s_addc_u32 s21, s47, 0
	s_add_u32 s22, s46, 0x4a00
	s_addc_u32 s23, s47, 0
	s_add_u32 s24, s46, 0x4b00
	s_addc_u32 s25, s47, 0
	s_add_u32 s26, s46, 0x4c00
	s_addc_u32 s27, s47, 0
	s_add_u32 s28, s46, 0x4d00
	s_addc_u32 s29, s47, 0
	s_add_u32 s30, s46, 0x4e00
	s_addc_u32 s31, s47, 0
	s_add_u32 s34, s46, 0x4f00
	s_addc_u32 s35, s47, 0
	s_add_u32 s36, s46, 0x5000
	s_addc_u32 s37, s47, 0
	s_add_u32 s38, s46, 0x5100
	s_addc_u32 s39, s47, 0
	s_add_u32 s40, s46, 0x5200
	s_addc_u32 s41, s47, 0
	s_add_u32 s42, s46, 0x5300
	s_addc_u32 s43, s47, 0
	s_mov_b32 s52, 1
	v_mov_b32_e32 v16, 0
	s_branch .LBB0_314

.LBB0_682:
	s_cmp_lt_i32 s48, 7
	s_cselect_b64 s[6:7], -1, 0
	s_add_u32 s36, s46, 0x4000000
	s_addc_u32 s37, s47, 0
	s_and_b64 s[6:7], s[6:7], s[4:5]
	v_mov_b32_e32 v0, v190
	s_andn2_b64 vcc, exec, s[6:7]
	s_cbranch_vccnz .LBB0_707
	v_readlane_b32 s98, v247, 2
	s_cmp_lt_u32 s98, 4
	s_cbranch_scc1 .Lstatprio6
	s_setprio 1

.LBB0_707:
	s_setprio 0
	s_load_dwordx2 s[38:39], s[0:1], 0xb0
	s_cmp_gt_i32 s49, 7
	s_cselect_b64 s[4:5], -1, 0
	s_and_b64 s[6:7], s[6:7], s[4:5]
	s_andn2_b64 vcc, exec, s[6:7]
	s_cbranch_vccnz .LBB0_761
	s_waitcnt vmcnt(0)
	s_waitcnt vmcnt(0) lgkmcnt(0)
	s_barrier
	s_and_saveexec_b64 s[6:7], s[44:45]
	s_cbranch_execz .LBB0_760
	s_add_i32 s8, 0, 0x21020
	v_mov_b32_e32 v0, s8
	s_waitcnt vmcnt(0) expcnt(0) lgkmcnt(0)
	ds_read_b32 v2, v0
	s_add_i32 s8, 0, 0x21024
	v_mov_b32_e32 v0, s8
	ds_read_b32 v0, v0
	s_waitcnt lgkmcnt(1)
	v_cmp_ne_u32_e32 vcc, 0, v2
	s_cbranch_vccnz .LBB0_724
	v_readlane_b32 s8, v247, 0
	v_readlane_b32 s9, v247, 1
	s_load_dwordx2 s[12:13], s[8:9], 0x4
	s_add_u32 s8, s46, 0x4200
	s_addc_u32 s9, s47, 0
	s_add_u32 s10, s46, 0x4400
	s_addc_u32 s11, s47, 0
	s_waitcnt lgkmcnt(0)
	s_mul_i32 s33, s12, s3
	s_add_u32 s12, s46, 0x4500
	s_mul_i32 s33, s33, s13
	s_addc_u32 s13, s47, 0
	s_add_u32 s14, s46, 0x4600
	s_addc_u32 s15, s47, 0
	s_add_u32 s16, s46, 0x4700
	s_addc_u32 s17, s47, 0
	s_add_u32 s18, s46, 0x4800
	s_addc_u32 s19, s47, 0
	s_add_u32 s20, s46, 0x4900
	s_addc_u32 s21, s47, 0
	s_add_u32 s22, s46, 0x4a00
	s_addc_u32 s23, s47, 0
	s_add_u32 s24, s46, 0x4b00
	s_addc_u32 s25, s47, 0
	s_add_u32 s26, s46, 0x4c00
	s_addc_u32 s27, s47, 0
	s_add_u32 s28, s46, 0x4d00
	s_addc_u32 s29, s47, 0
	s_add_u32 s30, s46, 0x4e00
	s_addc_u32 s31, s47, 0
	s_add_u32 s34, s46, 0x4f00
	s_addc_u32 s35, s47, 0
	s_add_u32 s40, s46, 0x5000
	s_addc_u32 s41, s47, 0
	s_add_u32 s42, s46, 0x5100
	s_addc_u32 s43, s47, 0
	s_add_u32 s60, s46, 0x5200
	s_addc_u32 s61, s47, 0
	s_add_u32 s62, s46, 0x5300
	s_addc_u32 s63, s47, 0
	s_mov_b32 s52, 1
	v_mov_b32_e32 v16, 0
	s_branch .LBB0_712

.LBB0_819:
	s_cmp_lt_i32 s48, 9
	s_cselect_b64 s[6:7], -1, 0
	s_and_b64 s[6:7], s[6:7], s[4:5]
	v_mov_b32_e32 v0, v190
	s_andn2_b64 vcc, exec, s[6:7]
	s_cbranch_vccnz .LBB0_844
	v_readlane_b32 s98, v247, 2
	s_cmp_lt_u32 s98, 4
	s_cbranch_scc1 .Lstatprio8
	s_setprio 1
.Lstatprio8:
	v_mov_b32_e32 v8, v190
	s_cmpk_gt_i32 s2, 0x7ff
	v_readfirstlane_b32 s12, v8
	s_cbranch_scc1 .LBB0_844
	s_ashr_i32 s60, s2, 31
	s_lshr_b32 s4, s60, 29
	s_add_i32 s9, s2, s4
	s_and_b32 s4, s9, -8
	s_sub_i32 s10, s2, s4
	s_cmp_gt_i32 s10, -1
	s_cbranch_scc0 .LBB0_823
	s_lshl_b32 s8, s10, 8
	s_cbranch_execz .LBB0_824
	s_branch .LBB0_825

.LBB0_844:
	s_setprio 0
	s_cmp_gt_i32 s49, 9
	s_cselect_b64 s[4:5], -1, 0
	s_and_b64 s[6:7], s[6:7], s[4:5]
	s_andn2_b64 vcc, exec, s[6:7]
	s_cbranch_vccnz .LBB0_898
	s_waitcnt vmcnt(0)
	s_waitcnt vmcnt(0) lgkmcnt(0)
	s_barrier
	s_and_saveexec_b64 s[6:7], s[44:45]
	s_cbranch_execz .LBB0_897
	s_add_i32 s8, 0, 0x21020
	v_mov_b32_e32 v0, s8
	s_waitcnt vmcnt(0) expcnt(0) lgkmcnt(0)
	ds_read_b32 v2, v0
	s_add_i32 s8, 0, 0x21024
	v_mov_b32_e32 v0, s8
	ds_read_b32 v0, v0
	s_waitcnt lgkmcnt(1)
	v_cmp_ne_u32_e32 vcc, 0, v2
	s_cbranch_vccnz .LBB0_861
	v_readlane_b32 s8, v247, 0
	v_readlane_b32 s9, v247, 1
	s_load_dwordx2 s[12:13], s[8:9], 0x4
	s_add_u32 s8, s46, 0x4200
	s_addc_u32 s9, s47, 0
	s_add_u32 s10, s46, 0x4400
	s_addc_u32 s11, s47, 0
	s_waitcnt lgkmcnt(0)
	s_mul_i32 s33, s12, s3
	s_add_u32 s12, s46, 0x4500
	s_mul_i32 s33, s33, s13
	s_addc_u32 s13, s47, 0
	s_add_u32 s14, s46, 0x4600
	s_addc_u32 s15, s47, 0
	s_add_u32 s16, s46, 0x4700
	s_addc_u32 s17, s47, 0
	s_add_u32 s18, s46, 0x4800
	s_addc_u32 s19, s47, 0
	s_add_u32 s20, s46, 0x4900
	s_addc_u32 s21, s47, 0
	s_add_u32 s22, s46, 0x4a00
	s_addc_u32 s23, s47, 0
	s_add_u32 s24, s46, 0x4b00
	s_addc_u32 s25, s47, 0
	s_add_u32 s26, s46, 0x4c00
	s_addc_u32 s27, s47, 0
	s_add_u32 s28, s46, 0x4d00
	s_addc_u32 s29, s47, 0
	s_add_u32 s30, s46, 0x4e00
	s_addc_u32 s31, s47, 0
	s_add_u32 s34, s46, 0x4f00
	s_addc_u32 s35, s47, 0
	s_add_u32 s40, s46, 0x5000
	s_addc_u32 s41, s47, 0
	s_add_u32 s42, s46, 0x5100
	s_addc_u32 s43, s47, 0
	s_add_u32 s60, s46, 0x5200
	s_addc_u32 s61, s47, 0
	s_add_u32 s62, s46, 0x5300
	s_addc_u32 s63, s47, 0
	s_mov_b32 s52, 1
	v_mov_b32_e32 v16, 0
	s_branch .LBB0_849

.LBB0_898:
	s_cmp_lt_i32 s48, 10
	s_cselect_b64 s[6:7], -1, 0
	s_and_b64 s[6:7], s[6:7], s[4:5]
	v_mov_b32_e32 v0, v190
	s_andn2_b64 vcc, exec, s[6:7]
	s_cbranch_vccnz .LBB0_923
	v_readlane_b32 s98, v247, 2
	s_cmp_lt_u32 s98, 4
	s_cbranch_scc1 .Lstatprio9
	s_setprio 1
.Lstatprio9:
	v_mov_b32_e32 v8, v190
	s_cmpk_gt_i32 s2, 0x1ff
	v_readfirstlane_b32 s12, v8
	s_cbranch_scc1 .LBB0_923
	s_ashr_i32 s52, s2, 31
	s_lshr_b32 s4, s52, 29
	s_add_i32 s9, s2, s4
	s_and_b32 s4, s9, -8
	s_sub_i32 s10, s2, s4
	s_cmp_gt_i32 s10, -1
	s_cbranch_scc0 .LBB0_902
	s_lshl_b32 s8, s10, 6
	s_cbranch_execz .LBB0_903
	s_branch .LBB0_904

.LBB0_923:
	s_setprio 0
	s_cmp_gt_i32 s49, 10
	s_cselect_b64 s[4:5], -1, 0
	s_and_b64 s[6:7], s[6:7], s[4:5]
	s_andn2_b64 vcc, exec, s[6:7]
	s_cbranch_vccnz .LBB0_977
	s_waitcnt vmcnt(0)
	s_waitcnt vmcnt(0) lgkmcnt(0)
	s_barrier
	s_and_saveexec_b64 s[6:7], s[44:45]
	s_cbranch_execz .LBB0_976
	s_add_i32 s8, 0, 0x21020
	v_mov_b32_e32 v0, s8
	s_waitcnt vmcnt(0) expcnt(0) lgkmcnt(0)
	ds_read_b32 v2, v0
	s_add_i32 s8, 0, 0x21024
	v_mov_b32_e32 v0, s8
	ds_read_b32 v0, v0
	s_waitcnt lgkmcnt(1)
	v_cmp_ne_u32_e32 vcc, 0, v2
	s_cbranch_vccnz .LBB0_940
	v_readlane_b32 s8, v247, 0
	v_readlane_b32 s9, v247, 1
	s_load_dwordx2 s[12:13], s[8:9], 0x4
	s_add_u32 s8, s46, 0x4200
	s_addc_u32 s9, s47, 0
	s_add_u32 s10, s46, 0x4400
	s_addc_u32 s11, s47, 0
	s_waitcnt lgkmcnt(0)
	s_mul_i32 s33, s12, s3
	s_add_u32 s12, s46, 0x4500
	s_mul_i32 s33, s33, s13
	s_addc_u32 s13, s47, 0
	s_add_u32 s14, s46, 0x4600
	s_addc_u32 s15, s47, 0
	s_add_u32 s16, s46, 0x4700
	s_addc_u32 s17, s47, 0
	s_add_u32 s18, s46, 0x4800
	s_addc_u32 s19, s47, 0
	s_add_u32 s20, s46, 0x4900
	s_addc_u32 s21, s47, 0
	s_add_u32 s22, s46, 0x4a00
	s_addc_u32 s23, s47, 0
	s_add_u32 s24, s46, 0x4b00
	s_addc_u32 s25, s47, 0
	s_add_u32 s26, s46, 0x4c00
	s_addc_u32 s27, s47, 0
	s_add_u32 s28, s46, 0x4d00
	s_addc_u32 s29, s47, 0
	s_add_u32 s30, s46, 0x4e00
	s_addc_u32 s31, s47, 0
	s_add_u32 s34, s46, 0x4f00
	s_addc_u32 s35, s47, 0
	s_add_u32 s40, s46, 0x5000
	s_addc_u32 s41, s47, 0
	s_add_u32 s42, s46, 0x5100
	s_addc_u32 s43, s47, 0
	s_add_u32 s60, s46, 0x5200
	s_addc_u32 s61, s47, 0
	s_add_u32 s62, s46, 0x5300
	s_addc_u32 s63, s47, 0
	s_mov_b32 s52, 1
	v_mov_b32_e32 v16, 0
	s_branch .LBB0_928

.LBB0_1035:
	s_cmp_lt_i32 s48, 12
	s_cselect_b64 s[6:7], -1, 0
	s_and_b64 s[6:7], s[6:7], s[4:5]
	v_mov_b32_e32 v0, v190
	s_andn2_b64 vcc, exec, s[6:7]
	s_cbranch_vccnz .LBB0_1084
	v_readlane_b32 s98, v247, 2
	s_cmp_lt_u32 s98, 4
	s_cbranch_scc1 .Lstatprio11
	s_setprio 1
.Lstatprio11:
	v_mov_b32_e32 v8, v190
	s_cmpk_lt_i32 s2, 0x100
	s_cselect_b64 s[8:9], -1, 0
	s_cmpk_gt_i32 s2, 0xff
	v_readfirstlane_b32 s14, v8
	s_cbranch_scc1 .LBB0_1060
	s_ashr_i32 s52, s2, 31
	s_lshr_b32 s4, s52, 29
	s_add_i32 s11, s2, s4
	s_and_b32 s4, s11, -8
	s_sub_i32 s12, s2, s4
	s_cmp_gt_i32 s12, -1
	s_cbranch_scc0 .LBB0_1039
	s_lshl_b32 s10, s12, 5
	s_cbranch_execz .LBB0_1040
	s_branch .LBB0_1041

.LBB0_1084:
	s_setprio 0
	s_cmp_gt_i32 s49, 12
	s_cselect_b64 s[4:5], -1, 0
	s_and_b64 s[6:7], s[6:7], s[4:5]
	s_andn2_b64 vcc, exec, s[6:7]
	s_cbranch_vccnz .LBB0_1138
	s_waitcnt vmcnt(0)
	s_waitcnt vmcnt(0) lgkmcnt(0)
	s_barrier
	s_and_saveexec_b64 s[6:7], s[44:45]
	s_cbranch_execz .LBB0_1137
	s_add_i32 s8, 0, 0x21020
	v_mov_b32_e32 v0, s8
	s_waitcnt vmcnt(0) expcnt(0) lgkmcnt(0)
	ds_read_b32 v2, v0
	s_add_i32 s8, 0, 0x21024
	v_mov_b32_e32 v0, s8
	ds_read_b32 v0, v0
	s_waitcnt lgkmcnt(1)
	v_cmp_ne_u32_e32 vcc, 0, v2
	s_cbranch_vccnz .LBB0_1101
	v_readlane_b32 s8, v247, 0
	v_readlane_b32 s9, v247, 1
	s_load_dwordx2 s[12:13], s[8:9], 0x4
	s_add_u32 s8, s46, 0x4200
	s_addc_u32 s9, s47, 0
	s_add_u32 s10, s46, 0x4400
	s_addc_u32 s11, s47, 0
	s_waitcnt lgkmcnt(0)
	s_mul_i32 s33, s12, s3
	s_add_u32 s12, s46, 0x4500
	s_mul_i32 s33, s33, s13
	s_addc_u32 s13, s47, 0
	s_add_u32 s14, s46, 0x4600
	s_addc_u32 s15, s47, 0
	s_add_u32 s16, s46, 0x4700
	s_addc_u32 s17, s47, 0
	s_add_u32 s18, s46, 0x4800
	s_addc_u32 s19, s47, 0
	s_add_u32 s20, s46, 0x4900
	s_addc_u32 s21, s47, 0
	s_add_u32 s22, s46, 0x4a00
	s_addc_u32 s23, s47, 0
	s_add_u32 s24, s46, 0x4b00
	s_addc_u32 s25, s47, 0
	s_add_u32 s26, s46, 0x4c00
	s_addc_u32 s27, s47, 0
	s_add_u32 s28, s46, 0x4d00
	s_addc_u32 s29, s47, 0
	s_add_u32 s30, s46, 0x4e00
	s_addc_u32 s31, s47, 0
	s_add_u32 s34, s46, 0x4f00
	s_addc_u32 s35, s47, 0
	s_add_u32 s42, s46, 0x5000
	s_addc_u32 s43, s47, 0
	s_add_u32 s60, s46, 0x5100
	s_addc_u32 s61, s47, 0
	s_add_u32 s62, s46, 0x5200
	s_addc_u32 s63, s47, 0
	s_add_u32 s64, s46, 0x5300
	s_addc_u32 s65, s47, 0
	s_mov_b32 s52, 1
	v_mov_b32_e32 v16, 0
	s_branch .LBB0_1089

.LBB0_1204:
	s_cmp_lt_i32 s48, 14
	s_cselect_b64 s[4:5], -1, 0
	s_and_b64 s[6:7], s[4:5], s[0:1]
	v_mov_b32_e32 v0, v190
	s_andn2_b64 vcc, exec, s[6:7]
	s_cbranch_vccnz .LBB0_1273
	v_readlane_b32 s98, v247, 2
	s_cmp_lt_u32 s98, 4
	s_cbranch_scc1 .Lstatprio13
	s_setprio 1
.Lstatprio13:
	s_add_u32 s70, s46, 0x14000000
	s_addc_u32 s71, s47, 0
	v_mov_b32_e32 v8, v190
	s_cmpk_lt_i32 s2, 0x200
	s_cselect_b64 s[4:5], -1, 0
	s_cmpk_gt_i32 s2, 0x1ff
	v_readfirstlane_b32 s14, v8
	s_cbranch_scc1 .LBB0_1229
	s_ashr_i32 s52, s2, 31
	s_lshr_b32 s0, s52, 29
	s_add_i32 s9, s2, s0
	s_and_b32 s0, s9, -8
	s_sub_i32 s10, s2, s0
	s_cmp_gt_i32 s10, -1
	s_cbranch_scc0 .LBB0_1208
	s_lshl_b32 s8, s10, 6
	s_cbranch_execz .LBB0_1209
	s_branch .LBB0_1210

.LBB0_1273:
	s_setprio 0
	s_cmp_gt_i32 s49, 14
	s_cselect_b64 s[0:1], -1, 0
	s_and_b64 s[4:5], s[6:7], s[0:1]
	s_andn2_b64 vcc, exec, s[4:5]
	s_cbranch_vccnz .LBB0_1327
	s_waitcnt vmcnt(0)
	s_waitcnt vmcnt(0) lgkmcnt(0)
	s_barrier
	s_and_saveexec_b64 s[4:5], s[44:45]
	s_cbranch_execz .LBB0_1326
	s_add_i32 s6, 0, 0x21020
	v_mov_b32_e32 v0, s6
	s_waitcnt vmcnt(0) expcnt(0) lgkmcnt(0)
	ds_read_b32 v2, v0
	s_add_i32 s6, 0, 0x21024
	v_mov_b32_e32 v0, s6
	ds_read_b32 v0, v0
	s_waitcnt lgkmcnt(1)
	v_cmp_ne_u32_e32 vcc, 0, v2
	s_cbranch_vccnz .LBB0_1290
	v_readlane_b32 s6, v247, 0
	v_readlane_b32 s7, v247, 1
	s_load_dwordx2 s[10:11], s[6:7], 0x4
	s_add_u32 s6, s46, 0x4200
	s_addc_u32 s7, s47, 0
	s_add_u32 s8, s46, 0x4400
	s_addc_u32 s9, s47, 0
	s_waitcnt lgkmcnt(0)
	s_mul_i32 s33, s10, s3
	s_add_u32 s10, s46, 0x4500
	s_mul_i32 s33, s33, s11
	s_addc_u32 s11, s47, 0
	s_add_u32 s12, s46, 0x4600
	s_addc_u32 s13, s47, 0
	s_add_u32 s14, s46, 0x4700
	s_addc_u32 s15, s47, 0
	s_add_u32 s16, s46, 0x4800
	s_addc_u32 s17, s47, 0
	s_add_u32 s18, s46, 0x4900
	s_addc_u32 s19, s47, 0
	s_add_u32 s20, s46, 0x4a00
	s_addc_u32 s21, s47, 0
	s_add_u32 s22, s46, 0x4b00
	s_addc_u32 s23, s47, 0
	s_add_u32 s24, s46, 0x4c00
	s_addc_u32 s25, s47, 0
	s_add_u32 s26, s46, 0x4d00
	s_addc_u32 s27, s47, 0
	s_add_u32 s28, s46, 0x4e00
	s_addc_u32 s29, s47, 0
	s_add_u32 s30, s46, 0x4f00
	s_addc_u32 s31, s47, 0
	s_add_u32 s34, s46, 0x5000
	s_addc_u32 s35, s47, 0
	s_add_u32 s42, s46, 0x5100
	s_addc_u32 s43, s47, 0
	s_add_u32 s60, s46, 0x5200
	s_addc_u32 s61, s47, 0
	s_add_u32 s62, s46, 0x5300
	s_addc_u32 s63, s47, 0
	s_mov_b32 s52, 1
	v_mov_b32_e32 v16, 0
	s_branch .LBB0_1278

.LBB0_1416:
	s_cmp_lt_i32 s48, 16
	s_cselect_b64 s[4:5], -1, 0
	s_and_b64 s[4:5], s[4:5], s[0:1]
	v_mov_b32_e32 v0, v190
	s_andn2_b64 vcc, exec, s[4:5]
	s_cbranch_vccnz .LBB0_1441
	v_readlane_b32 s98, v247, 2
	s_cmp_lt_u32 s98, 4
	s_cbranch_scc1 .Lstatprio15
	s_setprio 1
.Lstatprio15:
	v_mov_b32_e32 v8, v190
	s_cmpk_gt_i32 s2, 0x1ff
	v_readfirstlane_b32 s12, v8
	s_cbranch_scc1 .LBB0_1441
	s_ashr_i32 s52, s2, 31
	s_lshr_b32 s0, s52, 29
	s_add_i32 s7, s2, s0
	s_and_b32 s0, s7, -8
	s_sub_i32 s8, s2, s0
	s_cmp_gt_i32 s8, -1
	s_cbranch_scc0 .LBB0_1420
	s_lshl_b32 s6, s8, 6
	s_cbranch_execz .LBB0_1421
	s_branch .LBB0_1422

.LBB0_1441:
	s_setprio 0
	s_cmp_gt_i32 s49, 16
	s_cselect_b64 s[0:1], -1, 0
	s_and_b64 s[4:5], s[4:5], s[0:1]
	s_andn2_b64 vcc, exec, s[4:5]
	s_cbranch_vccnz .LBB0_1495
	s_waitcnt vmcnt(0)
	s_waitcnt vmcnt(0) lgkmcnt(0)
	s_barrier
	s_and_saveexec_b64 s[4:5], s[44:45]
	s_cbranch_execz .LBB0_1494
	s_add_i32 s6, 0, 0x21020
	v_mov_b32_e32 v0, s6
	s_waitcnt vmcnt(0) expcnt(0) lgkmcnt(0)
	ds_read_b32 v2, v0
	s_add_i32 s6, 0, 0x21024
	v_mov_b32_e32 v0, s6
	ds_read_b32 v0, v0
	s_waitcnt lgkmcnt(1)
	v_cmp_ne_u32_e32 vcc, 0, v2
	s_cbranch_vccnz .LBB0_1458
	v_readlane_b32 s6, v247, 0
	v_readlane_b32 s7, v247, 1
	s_load_dwordx2 s[10:11], s[6:7], 0x4
	s_add_u32 s6, s46, 0x4200
	s_addc_u32 s7, s47, 0
	s_add_u32 s8, s46, 0x4400
	s_addc_u32 s9, s47, 0
	s_waitcnt lgkmcnt(0)
	s_mul_i32 s33, s10, s3
	s_add_u32 s10, s46, 0x4500
	s_mul_i32 s33, s33, s11
	s_addc_u32 s11, s47, 0
	s_add_u32 s12, s46, 0x4600
	s_addc_u32 s13, s47, 0
	s_add_u32 s14, s46, 0x4700
	s_addc_u32 s15, s47, 0
	s_add_u32 s16, s46, 0x4800
	s_addc_u32 s17, s47, 0
	s_add_u32 s18, s46, 0x4900
	s_addc_u32 s19, s47, 0
	s_add_u32 s20, s46, 0x4a00
	s_addc_u32 s21, s47, 0
	s_add_u32 s22, s46, 0x4b00
	s_addc_u32 s23, s47, 0
	s_add_u32 s24, s46, 0x4c00
	s_addc_u32 s25, s47, 0
	s_add_u32 s26, s46, 0x4d00
	s_addc_u32 s27, s47, 0
	s_add_u32 s28, s46, 0x4e00
	s_addc_u32 s29, s47, 0
	s_add_u32 s30, s46, 0x4f00
	s_addc_u32 s31, s47, 0
	s_add_u32 s34, s46, 0x5000
	s_addc_u32 s35, s47, 0
	s_add_u32 s42, s46, 0x5100
	s_addc_u32 s43, s47, 0
	s_add_u32 s60, s46, 0x5200
	s_addc_u32 s61, s47, 0
	s_add_u32 s62, s46, 0x5300
	s_addc_u32 s63, s47, 0
	s_mov_b32 s52, 1
	v_mov_b32_e32 v16, 0
	s_branch .LBB0_1446

.LBB0_1553:
	s_cmp_lt_i32 s48, 18
	s_cselect_b64 s[4:5], -1, 0
	s_and_b64 s[4:5], s[4:5], s[0:1]
	v_mov_b32_e32 v0, v190
	s_andn2_b64 vcc, exec, s[4:5]
	s_cbranch_vccnz .LBB0_1578
	v_readlane_b32 s98, v247, 2
	s_cmp_lt_u32 s98, 4
	s_cbranch_scc1 .Lstatprio17
	s_setprio 1
.Lstatprio17:
	v_mov_b32_e32 v8, v190
	s_cmpk_gt_i32 s2, 0x7ff
	v_readfirstlane_b32 s10, v8
	s_cbranch_scc1 .LBB0_1578
	s_ashr_i32 s60, s2, 31
	s_lshr_b32 s0, s60, 29
	s_add_i32 s7, s2, s0
	s_and_b32 s0, s7, -8
	s_sub_i32 s8, s2, s0
	s_cmp_gt_i32 s8, -1
	s_cbranch_scc0 .LBB0_1557
	s_lshl_b32 s6, s8, 8
	s_cbranch_execz .LBB0_1558
	s_branch .LBB0_1559

.LBB0_1578:
	s_setprio 0
	s_cmp_gt_i32 s49, 18
	s_cselect_b64 s[0:1], -1, 0
	s_and_b64 s[4:5], s[4:5], s[0:1]
	s_andn2_b64 vcc, exec, s[4:5]
	s_cbranch_vccnz .LBB0_1632
	s_waitcnt vmcnt(0)
	s_waitcnt vmcnt(0) lgkmcnt(0)
	s_barrier
	s_and_saveexec_b64 s[4:5], s[44:45]
	s_cbranch_execz .LBB0_1631
	s_add_i32 s6, 0, 0x21020
	v_mov_b32_e32 v0, s6
	s_waitcnt vmcnt(0) expcnt(0) lgkmcnt(0)
	ds_read_b32 v2, v0
	s_add_i32 s6, 0, 0x21024
	v_mov_b32_e32 v0, s6
	ds_read_b32 v0, v0
	s_waitcnt lgkmcnt(1)
	v_cmp_ne_u32_e32 vcc, 0, v2
	s_cbranch_vccnz .LBB0_1595
	v_readlane_b32 s6, v247, 0
	v_readlane_b32 s7, v247, 1
	s_load_dwordx2 s[10:11], s[6:7], 0x4
	s_add_u32 s6, s46, 0x4200
	s_addc_u32 s7, s47, 0
	s_add_u32 s8, s46, 0x4400
	s_addc_u32 s9, s47, 0
	s_waitcnt lgkmcnt(0)
	s_mul_i32 s33, s10, s3
	s_add_u32 s10, s46, 0x4500
	s_mul_i32 s33, s33, s11
	s_addc_u32 s11, s47, 0
	s_add_u32 s12, s46, 0x4600
	s_addc_u32 s13, s47, 0
	s_add_u32 s14, s46, 0x4700
	s_addc_u32 s15, s47, 0
	s_add_u32 s16, s46, 0x4800
	s_addc_u32 s17, s47, 0
	s_add_u32 s18, s46, 0x4900
	s_addc_u32 s19, s47, 0
	s_add_u32 s20, s46, 0x4a00
	s_addc_u32 s21, s47, 0
	s_add_u32 s22, s46, 0x4b00
	s_addc_u32 s23, s47, 0
	s_add_u32 s24, s46, 0x4c00
	s_addc_u32 s25, s47, 0
	s_add_u32 s26, s46, 0x4d00
	s_addc_u32 s27, s47, 0
	s_add_u32 s28, s46, 0x4e00
	s_addc_u32 s29, s47, 0
	s_add_u32 s30, s46, 0x4f00
	s_addc_u32 s31, s47, 0
	s_add_u32 s34, s46, 0x5000
	s_addc_u32 s35, s47, 0
	s_add_u32 s42, s46, 0x5100
	s_addc_u32 s43, s47, 0
	s_add_u32 s58, s46, 0x5200
	s_addc_u32 s59, s47, 0
	s_add_u32 s60, s46, 0x5300
	s_addc_u32 s61, s47, 0
	s_mov_b32 s52, 1
	v_mov_b32_e32 v16, 0
	s_branch .LBB0_1583

.LBB0_1632:
	s_cmp_lt_i32 s48, 19
	s_cselect_b64 s[4:5], -1, 0
	s_and_b64 s[4:5], s[4:5], s[0:1]
	v_mov_b32_e32 v0, v190
	s_andn2_b64 vcc, exec, s[4:5]
	s_cbranch_vccnz .LBB0_1657
	v_readlane_b32 s98, v247, 2
	s_cmp_lt_u32 s98, 4
	s_cbranch_scc1 .Lstatprio18
	s_setprio 1
.Lstatprio18:
	v_mov_b32_e32 v8, v190
	s_cmpk_gt_i32 s2, 0x1ff
	v_readfirstlane_b32 s10, v8
	s_cbranch_scc1 .LBB0_1657
	s_ashr_i32 s52, s2, 31
	s_lshr_b32 s0, s52, 29
	s_add_i32 s8, s2, s0
	s_and_b32 s0, s8, -8
	s_sub_i32 s7, s2, s0
	s_cmp_gt_i32 s7, -1
	s_cbranch_scc0 .LBB0_1636
	s_lshl_b32 s6, s7, 6
	s_ashr_i32 s0, s8, 3
	s_cbranch_execz .LBB0_1637
	s_branch .LBB0_1638

.LBB0_1657:
	s_setprio 0
	s_cmp_gt_i32 s49, 19
	s_cselect_b64 s[0:1], -1, 0
	s_and_b64 s[4:5], s[4:5], s[0:1]
	s_andn2_b64 vcc, exec, s[4:5]
	s_cbranch_vccnz .LBB0_1711
	s_waitcnt vmcnt(0)
	s_waitcnt vmcnt(0) lgkmcnt(0)
	s_barrier
	s_and_saveexec_b64 s[4:5], s[44:45]
	s_cbranch_execz .LBB0_1710
	s_add_i32 s6, 0, 0x21020
	v_mov_b32_e32 v0, s6
	s_waitcnt vmcnt(0) expcnt(0) lgkmcnt(0)
	ds_read_b32 v2, v0
	s_add_i32 s6, 0, 0x21024
	v_mov_b32_e32 v0, s6
	ds_read_b32 v0, v0
	s_waitcnt lgkmcnt(1)
	v_cmp_ne_u32_e32 vcc, 0, v2
	s_cbranch_vccnz .LBB0_1674
	v_readlane_b32 s6, v247, 0
	v_readlane_b32 s7, v247, 1
	s_load_dwordx2 s[10:11], s[6:7], 0x4
	s_add_u32 s6, s46, 0x4200
	s_addc_u32 s7, s47, 0
	s_add_u32 s8, s46, 0x4400
	s_addc_u32 s9, s47, 0
	s_waitcnt lgkmcnt(0)
	s_mul_i32 s33, s10, s3
	s_add_u32 s10, s46, 0x4500
	s_mul_i32 s33, s33, s11
	s_addc_u32 s11, s47, 0
	s_add_u32 s12, s46, 0x4600
	s_addc_u32 s13, s47, 0
	s_add_u32 s14, s46, 0x4700
	s_addc_u32 s15, s47, 0
	s_add_u32 s16, s46, 0x4800
	s_addc_u32 s17, s47, 0
	s_add_u32 s18, s46, 0x4900
	s_addc_u32 s19, s47, 0
	s_add_u32 s20, s46, 0x4a00
	s_addc_u32 s21, s47, 0
	s_add_u32 s22, s46, 0x4b00
	s_addc_u32 s23, s47, 0
	s_add_u32 s24, s46, 0x4c00
	s_addc_u32 s25, s47, 0
	s_add_u32 s26, s46, 0x4d00
	s_addc_u32 s27, s47, 0
	s_add_u32 s28, s46, 0x4e00
	s_addc_u32 s29, s47, 0
	s_add_u32 s30, s46, 0x4f00
	s_addc_u32 s31, s47, 0
	s_add_u32 s34, s46, 0x5000
	s_addc_u32 s35, s47, 0
	s_add_u32 s42, s46, 0x5100
	s_addc_u32 s43, s47, 0
	s_add_u32 s44, s46, 0x5200
	s_addc_u32 s45, s47, 0
	s_add_u32 s52, s46, 0x5300
	s_addc_u32 s53, s47, 0
	s_mov_b32 s49, 1
	v_mov_b32_e32 v16, 0
	s_branch .LBB0_1662
